# P3 SST scan loads default policy instead of nt, on top of v111
# speedup vs baseline: 1.0206x; 1.0206x over previous
.LBB0_477:
	v_add_co_u32_e32 v6, vcc, 0xfff88000, v2
	v_cvt_pk_bf16_f32 v22, v4, v5
	s_nop 0
	v_addc_co_u32_e32 v7, vcc, -1, v3, vcc
	v_add_co_u32_e32 v18, vcc, 0xfff90000, v2
	v_add_co_u32_e64 v14, s[0:1], s22, v2
	s_nop 0
	v_addc_co_u32_e32 v19, vcc, -1, v3, vcc
	v_add_co_u32_e32 v20, vcc, 0xfff98000, v2
	global_load_dword v43, v[6:7], off
	global_load_dword v44, v[18:19], off
	v_addc_co_u32_e32 v21, vcc, -1, v3, vcc
	v_add_co_u32_e32 v6, vcc, 0xfffa0000, v2
	v_addc_co_u32_e64 v15, s[0:1], -1, v3, s[0:1]
	s_nop 0
	v_addc_co_u32_e32 v7, vcc, -1, v3, vcc
	v_add_co_u32_e32 v18, vcc, 0xfffa8000, v2
	global_load_dword v45, v[20:21], off
	global_load_dword v46, v[6:7], off
	v_addc_co_u32_e32 v19, vcc, -1, v3, vcc
	v_add_co_u32_e32 v6, vcc, 0xfffb0000, v2
	v_add_co_u32_e64 v16, s[0:1], s23, v2
	s_nop 0
	v_addc_co_u32_e32 v7, vcc, -1, v3, vcc
	v_add_co_u32_e32 v20, vcc, 0xfffb8000, v2
	global_load_dword v47, v[18:19], off
	global_load_dword v48, v[6:7], off
	v_addc_co_u32_e32 v21, vcc, -1, v3, vcc
	v_add_co_u32_e32 v6, vcc, 0xfffc0000, v2
	v_addc_co_u32_e64 v17, s[0:1], -1, v3, s[0:1]
	s_nop 0
	v_addc_co_u32_e32 v7, vcc, -1, v3, vcc
	v_add_co_u32_e32 v18, vcc, 0xfffc8000, v2
	global_load_dword v49, v[20:21], off
	global_load_dword v50, v[6:7], off
	v_addc_co_u32_e32 v19, vcc, -1, v3, vcc
	v_add_co_u32_e32 v6, vcc, 0xfffd0000, v2
	global_load_dword v51, v[18:19], off
	s_nop 0
	v_addc_co_u32_e32 v7, vcc, -1, v3, vcc
	v_add_co_u32_e32 v18, vcc, 0xfffd8000, v2
	s_add_i32 s29, s29, 16
	s_nop 0
	v_addc_co_u32_e32 v19, vcc, -1, v3, vcc
	v_add_co_u32_e32 v20, vcc, 0xfffe0000, v2
	global_load_dword v52, v[6:7], off
	global_load_dword v53, v[18:19], off
	v_addc_co_u32_e32 v21, vcc, -1, v3, vcc
	v_add_co_u32_e32 v6, vcc, 0xfffe8000, v2
	s_cmp_gt_u32 s29, 47
	s_nop 0
	v_addc_co_u32_e32 v7, vcc, -1, v3, vcc
	v_add_co_u32_e32 v18, vcc, 0xffff0000, v2
	global_load_dword v54, v[20:21], off
	global_load_dword v55, v[6:7], off
	v_addc_co_u32_e32 v19, vcc, -1, v3, vcc
	v_add_co_u32_e32 v6, vcc, 0xffff8000, v2
	s_waitcnt vmcnt(12)
	v_lshlrev_b32_e32 v42, 16, v43
	v_addc_co_u32_e32 v7, vcc, -1, v3, vcc
	global_load_dword v56, v[18:19], off
	global_load_dword v57, v[6:7], off
	global_load_dword v58, v[2:3], off
	v_add_co_u32_e32 v20, vcc, 0xfbf88000, v2
	v_and_b32_e32 v43, 0xffff0000, v43
	s_nop 0
	v_addc_co_u32_e32 v21, vcc, -1, v3, vcc
	v_add_co_u32_e32 v6, vcc, 0xfbf90000, v2
	global_store_dword v[20:21], v22, off
	s_nop 0
	v_addc_co_u32_e32 v7, vcc, -1, v3, vcc
	v_add_co_u32_e32 v18, vcc, 0xfbf98000, v2
	v_pk_fma_f32 v[4:5], v[0:1], v[4:5], v[42:43]
	s_nop 0
	v_addc_co_u32_e32 v19, vcc, -1, v3, vcc
	v_add_co_u32_e32 v20, vcc, 0xfbfa0000, v2
	s_waitcnt vmcnt(15)
	v_lshlrev_b32_e32 v42, 16, v44
	v_addc_co_u32_e32 v21, vcc, -1, v3, vcc
	v_add_co_u32_e32 v22, vcc, 0xfbfa8000, v2
	v_and_b32_e32 v43, 0xffff0000, v44
	s_nop 0
	v_addc_co_u32_e32 v23, vcc, -1, v3, vcc
	v_add_co_u32_e32 v24, vcc, 0xfbfb0000, v2
	v_cvt_pk_bf16_f32 v44, v4, v5
	s_nop 0
	v_addc_co_u32_e32 v25, vcc, -1, v3, vcc
	v_add_co_u32_e32 v26, vcc, 0xfbfb8000, v2
	v_pk_fma_f32 v[4:5], v[0:1], v[4:5], v[42:43]
	s_nop 0
	v_addc_co_u32_e32 v27, vcc, -1, v3, vcc
	s_waitcnt vmcnt(14)
	v_lshlrev_b32_e32 v42, 16, v45
	v_and_b32_e32 v43, 0xffff0000, v45
	v_add_co_u32_e32 v28, vcc, 0xfbfc0000, v2
	global_store_dword v[6:7], v44, off
	v_cvt_pk_bf16_f32 v44, v4, v5
	v_pk_fma_f32 v[4:5], v[0:1], v[4:5], v[42:43]
	s_waitcnt vmcnt(14)
	v_lshlrev_b32_e32 v6, 16, v46
	v_and_b32_e32 v7, 0xffff0000, v46
	v_addc_co_u32_e32 v29, vcc, -1, v3, vcc
	global_store_dword v[18:19], v44, off
	v_cvt_pk_bf16_f32 v18, v4, v5
	v_pk_fma_f32 v[4:5], v[0:1], v[4:5], v[6:7]
	s_waitcnt vmcnt(14)
	v_lshlrev_b32_e32 v6, 16, v47
	v_and_b32_e32 v7, 0xffff0000, v47
	v_add_co_u32_e32 v30, vcc, 0xfbfc8000, v2
	global_store_dword v[20:21], v18, off
	v_cvt_pk_bf16_f32 v18, v4, v5
	v_pk_fma_f32 v[4:5], v[0:1], v[4:5], v[6:7]
	s_waitcnt vmcnt(14)
	v_lshlrev_b32_e32 v6, 16, v48
	v_and_b32_e32 v7, 0xffff0000, v48
	v_addc_co_u32_e32 v31, vcc, -1, v3, vcc
	global_store_dword v[22:23], v18, off
	v_cvt_pk_bf16_f32 v18, v4, v5
	v_pk_fma_f32 v[4:5], v[0:1], v[4:5], v[6:7]
	s_waitcnt vmcnt(14)
	v_lshlrev_b32_e32 v6, 16, v49
	v_and_b32_e32 v7, 0xffff0000, v49
	v_add_co_u32_e32 v32, vcc, 0xfbfd0000, v2
	global_store_dword v[24:25], v18, off
	v_cvt_pk_bf16_f32 v18, v4, v5
	v_pk_fma_f32 v[4:5], v[0:1], v[4:5], v[6:7]
	s_waitcnt vmcnt(14)
	v_lshlrev_b32_e32 v6, 16, v50
	v_and_b32_e32 v7, 0xffff0000, v50
	v_addc_co_u32_e32 v33, vcc, -1, v3, vcc
	global_store_dword v[26:27], v18, off
	v_cvt_pk_bf16_f32 v18, v4, v5
	v_pk_fma_f32 v[4:5], v[0:1], v[4:5], v[6:7]
	s_waitcnt vmcnt(14)
	v_lshlrev_b32_e32 v6, 16, v51
	v_and_b32_e32 v7, 0xffff0000, v51
	v_add_co_u32_e32 v34, vcc, 0xfbfd8000, v2
	global_store_dword v[28:29], v18, off
	v_cvt_pk_bf16_f32 v18, v4, v5
	v_pk_fma_f32 v[4:5], v[0:1], v[4:5], v[6:7]
	s_waitcnt vmcnt(14)
	v_lshlrev_b32_e32 v6, 16, v52
	v_and_b32_e32 v7, 0xffff0000, v52
	v_addc_co_u32_e32 v35, vcc, -1, v3, vcc
	global_store_dword v[30:31], v18, off
	v_cvt_pk_bf16_f32 v18, v4, v5
	v_pk_fma_f32 v[4:5], v[0:1], v[4:5], v[6:7]
	s_waitcnt vmcnt(14)
	v_lshlrev_b32_e32 v6, 16, v53
	v_and_b32_e32 v7, 0xffff0000, v53
	v_add_co_u32_e32 v36, vcc, s26, v2
	global_store_dword v[32:33], v18, off
	v_cvt_pk_bf16_f32 v20, v4, v5
	s_waitcnt vmcnt(14)
	v_lshlrev_b32_e32 v18, 16, v54
	v_and_b32_e32 v19, 0xffff0000, v54
	v_pk_fma_f32 v[4:5], v[0:1], v[4:5], v[6:7]
	v_addc_co_u32_e32 v37, vcc, -1, v3, vcc
	global_store_dword v[34:35], v20, off
	s_waitcnt vmcnt(14)
	v_lshlrev_b32_e32 v6, 16, v55
	v_and_b32_e32 v7, 0xffff0000, v55
	v_cvt_pk_bf16_f32 v20, v4, v5
	v_pk_fma_f32 v[4:5], v[0:1], v[4:5], v[18:19]
	v_add_co_u32_e32 v38, vcc, s27, v2
	s_waitcnt vmcnt(13)
	v_lshlrev_b32_e32 v18, 16, v56
	v_and_b32_e32 v19, 0xffff0000, v56
	global_store_dword v[14:15], v20, off
	v_cvt_pk_bf16_f32 v20, v4, v5
	v_pk_fma_f32 v[4:5], v[0:1], v[4:5], v[6:7]
	v_addc_co_u32_e32 v39, vcc, -1, v3, vcc
	s_waitcnt vmcnt(13)
	v_lshlrev_b32_e32 v6, 16, v57
	v_and_b32_e32 v7, 0xffff0000, v57
	global_store_dword v[16:17], v20, off
	v_cvt_pk_bf16_f32 v16, v4, v5
	v_pk_fma_f32 v[4:5], v[0:1], v[4:5], v[18:19]
	v_add_co_u32_e32 v40, vcc, 0xfc000000, v2
	s_waitcnt vmcnt(13)
	v_lshlrev_b32_e32 v14, 16, v58
	v_and_b32_e32 v15, 0xffff0000, v58
	global_store_dword v[36:37], v16, off
	v_cvt_pk_bf16_f32 v16, v4, v5
	v_pk_fma_f32 v[4:5], v[0:1], v[4:5], v[6:7]
	v_addc_co_u32_e32 v41, vcc, -1, v3, vcc
	v_lshl_add_u64 v[2:3], v[2:3], 0, s[10:11]
	v_cvt_pk_bf16_f32 v6, v4, v5
	v_pk_fma_f32 v[4:5], v[0:1], v[4:5], v[14:15]
	global_store_dword v[38:39], v16, off
	global_store_dword v[40:41], v6, off
	s_cbranch_scc0 .LBB0_477
	v_add_u32_e32 v8, s3, v8
	v_cmp_lt_i32_e32 vcc, s28, v8
	s_or_b64 s[8:9], vcc, s[8:9]
	v_add_u32_e32 v9, s12, v9
	s_andn2_b64 exec, exec, s[8:9]
	s_cbranch_execnz .LBB0_476
